# states / decays read with sc1 (L1 bypass) in scan and MIX3; L1 invalidate dropped at the two full barriers around the scan phase
# speedup vs baseline: 1.0863x; 1.0050x over previous
.Lsc_il_pr:
	s_cmp_ge_u32 s94, 8
	s_cbranch_scc1 .Lsc_id_pr
	s_add_i32 s72, s89, 2
	s_cmp_ge_u32 s94, s72
	s_cbranch_scc1 .Lsc_id_pr
	s_lshl_b32 s70, s94, 21
	s_mov_b32 s71, 0
	v_lshl_add_u64 v[248:249], s[70:71], 0, v[166:167]
	s_and_b32 s70, s94, 1
	s_lshl_b32 s70, s70, 12
	s_add_i32 s70, s70, s73
	s_mov_b32 s100, 0x20000
	s_mov_b32 s101, 0
	s_mov_b32 m0, s70
	s_add_i32 s70, s70, 0x100
	global_load_lds_dword v[248:249], off sc1
	v_lshl_add_u64 v[248:249], v[248:249], 0, s[100:101]
	s_mov_b32 m0, s70
	s_add_i32 s70, s70, 0x100
	global_load_lds_dword v[248:249], off sc1
	v_lshl_add_u64 v[248:249], v[248:249], 0, s[100:101]
	s_mov_b32 m0, s70
	s_add_i32 s70, s70, 0x100
	global_load_lds_dword v[248:249], off sc1
	v_lshl_add_u64 v[248:249], v[248:249], 0, s[100:101]
	s_mov_b32 m0, s70
	s_add_i32 s70, s70, 0x100
	global_load_lds_dword v[248:249], off sc1
	v_lshl_add_u64 v[248:249], v[248:249], 0, s[100:101]
	s_mov_b32 m0, s70
	s_add_i32 s70, s70, 0x100
	global_load_lds_dword v[248:249], off sc1
	v_lshl_add_u64 v[248:249], v[248:249], 0, s[100:101]
	s_mov_b32 m0, s70
	s_add_i32 s70, s70, 0x100
	global_load_lds_dword v[248:249], off sc1
	v_lshl_add_u64 v[248:249], v[248:249], 0, s[100:101]
	s_mov_b32 m0, s70
	s_add_i32 s70, s70, 0x100
	global_load_lds_dword v[248:249], off sc1
	v_lshl_add_u64 v[248:249], v[248:249], 0, s[100:101]
	s_mov_b32 m0, s70
	s_add_i32 s70, s70, 0x100
	global_load_lds_dword v[248:249], off sc1
	v_lshl_add_u64 v[248:249], v[248:249], 0, s[100:101]
	s_mov_b32 m0, s70
	s_add_i32 s70, s70, 0x100
	global_load_lds_dword v[248:249], off sc1
	v_lshl_add_u64 v[248:249], v[248:249], 0, s[100:101]
	s_mov_b32 m0, s70
	s_add_i32 s70, s70, 0x100
	global_load_lds_dword v[248:249], off sc1
	v_lshl_add_u64 v[248:249], v[248:249], 0, s[100:101]
	s_mov_b32 m0, s70
	s_add_i32 s70, s70, 0x100
	global_load_lds_dword v[248:249], off sc1
	v_lshl_add_u64 v[248:249], v[248:249], 0, s[100:101]
	s_mov_b32 m0, s70
	s_add_i32 s70, s70, 0x100
	global_load_lds_dword v[248:249], off sc1
	v_lshl_add_u64 v[248:249], v[248:249], 0, s[100:101]
	s_mov_b32 m0, s70
	s_add_i32 s70, s70, 0x100
	global_load_lds_dword v[248:249], off sc1
	v_lshl_add_u64 v[248:249], v[248:249], 0, s[100:101]
	s_mov_b32 m0, s70
	s_add_i32 s70, s70, 0x100
	global_load_lds_dword v[248:249], off sc1
	v_lshl_add_u64 v[248:249], v[248:249], 0, s[100:101]
	s_mov_b32 m0, s70
	s_add_i32 s70, s70, 0x100
	global_load_lds_dword v[248:249], off sc1
	v_lshl_add_u64 v[248:249], v[248:249], 0, s[100:101]
	s_mov_b32 m0, s70
	s_add_i32 s70, s70, 0x100
	global_load_lds_dword v[248:249], off sc1
	s_add_i32 s94, s94, 1
	s_mov_b32 s95, 1
	s_branch .Lsc_il_pr

.LBB0_38:
	s_cmp_lg_u32 s88, 0
	s_cbranch_scc1 .Lsc_nodec
	s_cmp_ge_u32 s89, 8
	s_cbranch_scc1 .Lsc_nodec
	v_and_b32_e32 v241, 15, v229
	s_lshl_b32 s70, s89, 4
	v_add_u32_e32 v241, s70, v241
	v_lshlrev_b32_e32 v241, 5, v241
	global_load_dword v241, v241, s[58:59] sc1

.Lsc_noscan:
	s_add_i32 s89, s89, 1
	v_add_f32_e32 v98, 0, v107
	v_add_f32_e32 v99, 0, v149
	v_add_f32_e32 v98, v139, v98
	v_add_f32_e32 v99, v150, v99
	v_add_f32_e32 v98, v144, v98
	v_add_f32_e32 v99, v151, v99
	v_add_f32_e32 v98, v145, v98
	v_add_f32_e32 v99, v129, v99
	v_add_f32_e32 v98, v146, v98
	v_add_f32_e32 v99, v152, v99
	v_add_f32_e32 v98, v147, v98
	v_add_f32_e32 v99, v153, v99
	v_pk_add_f32 v[98:99], v[126:127], v[98:99]
	s_andn2_b64 s[36:37], s[36:37], exec
	v_pk_add_f32 v[98:99], v[124:125], v[98:99]
	s_and_b64 s[50:51], s[34:35], exec
	v_pk_add_f32 v[98:99], v[122:123], v[98:99]
	v_mov_b32_e32 v107, v128
	v_pk_add_f32 v[98:99], v[120:121], v[98:99]
	s_add_i32 s38, s23, 1
	v_pk_add_f32 v[98:99], v[118:119], v[98:99]
	s_add_i32 s17, s17, 64
	v_pk_add_f32 v[98:99], v[116:117], v[98:99]
	s_or_b64 s[36:37], s[36:37], s[50:51]
	v_pk_add_f32 v[98:99], v[114:115], v[98:99]
	s_cmp_gt_i32 s23, 7
	v_pk_add_f32 v[98:99], v[112:113], v[98:99]
	v_subrev_u32_e32 v201, 64, v201
	v_pk_add_f32 v[98:99], v[110:111], v[98:99]
	s_nop 0
	v_pk_add_f32 v[98:99], v[108:109], v[98:99]
	s_barrier
	v_pk_fma_f32 v[184:185], v[184:185], v[106:107], v[98:99]
	s_cbranch_scc1 .LBB0_34
	v_mov_b32_e32 v181, v138
	v_mov_b32_e32 v175, v148
	s_mov_b32 s23, s38
	s_cmp_lg_u32 s88, 0
	s_cbranch_scc0 .Lsc_tl_sc
	s_mov_b32 s95, 0
	s_cmp_ge_u32 s94, 8
	s_cbranch_scc1 .LBB0_36
	s_lshl_b32 s70, s94, 21
	s_mov_b32 s71, 0
	v_lshl_add_u64 v[248:249], s[70:71], 0, v[166:167]
	s_and_b32 s70, s94, 1
	s_lshl_b32 s70, s70, 12
	s_add_i32 s70, s70, s73
	s_mov_b32 s100, 0x20000
	s_mov_b32 s101, 0
	s_mov_b32 m0, s70
	s_add_i32 s70, s70, 0x100
	global_load_lds_dword v[248:249], off sc1
	v_lshl_add_u64 v[248:249], v[248:249], 0, s[100:101]
	s_mov_b32 m0, s70
	s_add_i32 s70, s70, 0x100
	global_load_lds_dword v[248:249], off sc1
	v_lshl_add_u64 v[248:249], v[248:249], 0, s[100:101]
	s_mov_b32 m0, s70
	s_add_i32 s70, s70, 0x100
	global_load_lds_dword v[248:249], off sc1
	v_lshl_add_u64 v[248:249], v[248:249], 0, s[100:101]
	s_mov_b32 m0, s70
	s_add_i32 s70, s70, 0x100
	global_load_lds_dword v[248:249], off sc1
	v_lshl_add_u64 v[248:249], v[248:249], 0, s[100:101]
	s_mov_b32 m0, s70
	s_add_i32 s70, s70, 0x100
	global_load_lds_dword v[248:249], off sc1
	v_lshl_add_u64 v[248:249], v[248:249], 0, s[100:101]
	s_mov_b32 m0, s70
	s_add_i32 s70, s70, 0x100
	global_load_lds_dword v[248:249], off sc1
	v_lshl_add_u64 v[248:249], v[248:249], 0, s[100:101]
	s_mov_b32 m0, s70
	s_add_i32 s70, s70, 0x100
	global_load_lds_dword v[248:249], off sc1
	v_lshl_add_u64 v[248:249], v[248:249], 0, s[100:101]
	s_mov_b32 m0, s70
	s_add_i32 s70, s70, 0x100
	global_load_lds_dword v[248:249], off sc1
	v_lshl_add_u64 v[248:249], v[248:249], 0, s[100:101]
	s_mov_b32 m0, s70
	s_add_i32 s70, s70, 0x100
	global_load_lds_dword v[248:249], off sc1
	v_lshl_add_u64 v[248:249], v[248:249], 0, s[100:101]
	s_mov_b32 m0, s70
	s_add_i32 s70, s70, 0x100
	global_load_lds_dword v[248:249], off sc1
	v_lshl_add_u64 v[248:249], v[248:249], 0, s[100:101]
	s_mov_b32 m0, s70
	s_add_i32 s70, s70, 0x100
	global_load_lds_dword v[248:249], off sc1
	v_lshl_add_u64 v[248:249], v[248:249], 0, s[100:101]
	s_mov_b32 m0, s70
	s_add_i32 s70, s70, 0x100
	global_load_lds_dword v[248:249], off sc1
	v_lshl_add_u64 v[248:249], v[248:249], 0, s[100:101]
	s_mov_b32 m0, s70
	s_add_i32 s70, s70, 0x100
	global_load_lds_dword v[248:249], off sc1
	v_lshl_add_u64 v[248:249], v[248:249], 0, s[100:101]
	s_mov_b32 m0, s70
	s_add_i32 s70, s70, 0x100
	global_load_lds_dword v[248:249], off sc1
	v_lshl_add_u64 v[248:249], v[248:249], 0, s[100:101]
	s_mov_b32 m0, s70
	s_add_i32 s70, s70, 0x100
	global_load_lds_dword v[248:249], off sc1
	v_lshl_add_u64 v[248:249], v[248:249], 0, s[100:101]
	s_mov_b32 m0, s70
	s_add_i32 s70, s70, 0x100
	global_load_lds_dword v[248:249], off sc1
	s_add_i32 s94, s94, 1
	s_add_i32 s72, s89, 2
	s_cmp_ge_u32 s94, s72
	s_cselect_b32 s95, 1, 0
	s_branch .LBB0_36

.Lsc_lo_b1:
	s_barrier
	s_cmp_lg_u32 s88, 0
	s_cbranch_scc1 .Lsc_lo_b2
	v_and_b32_e32 v241, 15, v229
	s_lshl_b32 s70, s89, 4
	v_add_u32_e32 v241, s70, v241
	v_lshlrev_b32_e32 v241, 5, v241
	global_load_dword v241, v241, s[58:59] sc1
	s_waitcnt vmcnt(0)
	s_and_b32 s70, s89, 1
	s_lshl_b32 s70, s70, 12
	v_add_u32_e32 v247, s70, v246
	ds_read_b32 v2, v247
	ds_read_b32 v3, v247 offset:256
	ds_read_b32 v4, v247 offset:512
	ds_read_b32 v5, v247 offset:768
	ds_read_b32 v6, v247 offset:1024
	ds_read_b32 v7, v247 offset:1280
	ds_read_b32 v8, v247 offset:1536
	ds_read_b32 v9, v247 offset:1792
	ds_read_b32 v10, v247 offset:2048
	ds_read_b32 v11, v247 offset:2304
	ds_read_b32 v12, v247 offset:2560
	ds_read_b32 v13, v247 offset:2816
	ds_read_b32 v14, v247 offset:3072
	ds_read_b32 v15, v247 offset:3328
	ds_read_b32 v16, v247 offset:3584
	ds_read_b32 v17, v247 offset:3840
	s_lshl_b32 s70, s89, 21
	s_mov_b32 s71, 0
	v_lshl_add_u64 v[98:99], s[70:71], 0, v[166:167]
	s_mov_b32 s100, 0x20000
	s_mov_b32 s101, 0
	s_waitcnt lgkmcnt(0)
	v_readlane_b32 s70, v241, 0
	v_cvt_pk_bf16_f32 v100, v177, v176
	global_store_dword v[98:99], v100, off
	v_lshlrev_b32_e32 v101, 16, v2
	v_and_b32_e32 v102, 0xffff0000, v2
	v_readlane_b32 s71, v241, 1
	v_fma_f32 v177, v177, s70, v101
	v_fma_f32 v176, v176, s70, v102
	v_lshl_add_u64 v[98:99], v[98:99], 0, s[100:101]
	v_cvt_pk_bf16_f32 v100, v177, v176
	global_store_dword v[98:99], v100, off
	v_lshlrev_b32_e32 v101, 16, v3
	v_and_b32_e32 v102, 0xffff0000, v3
	v_readlane_b32 s70, v241, 2
	v_fma_f32 v177, v177, s71, v101
	v_fma_f32 v176, v176, s71, v102
	v_lshl_add_u64 v[98:99], v[98:99], 0, s[100:101]
	v_cvt_pk_bf16_f32 v100, v177, v176
	global_store_dword v[98:99], v100, off
	v_lshlrev_b32_e32 v101, 16, v4
	v_and_b32_e32 v102, 0xffff0000, v4
	v_readlane_b32 s71, v241, 3
	v_fma_f32 v177, v177, s70, v101
	v_fma_f32 v176, v176, s70, v102
	v_lshl_add_u64 v[98:99], v[98:99], 0, s[100:101]
	v_cvt_pk_bf16_f32 v100, v177, v176
	global_store_dword v[98:99], v100, off
	v_lshlrev_b32_e32 v101, 16, v5
	v_and_b32_e32 v102, 0xffff0000, v5
	v_readlane_b32 s70, v241, 4
	v_fma_f32 v177, v177, s71, v101
	v_fma_f32 v176, v176, s71, v102
	v_lshl_add_u64 v[98:99], v[98:99], 0, s[100:101]
	v_cvt_pk_bf16_f32 v100, v177, v176
	global_store_dword v[98:99], v100, off
	v_lshlrev_b32_e32 v101, 16, v6
	v_and_b32_e32 v102, 0xffff0000, v6
	v_readlane_b32 s71, v241, 5
	v_fma_f32 v177, v177, s70, v101
	v_fma_f32 v176, v176, s70, v102
	v_lshl_add_u64 v[98:99], v[98:99], 0, s[100:101]
	v_cvt_pk_bf16_f32 v100, v177, v176
	global_store_dword v[98:99], v100, off
	v_lshlrev_b32_e32 v101, 16, v7
	v_and_b32_e32 v102, 0xffff0000, v7
	v_readlane_b32 s70, v241, 6
	v_fma_f32 v177, v177, s71, v101
	v_fma_f32 v176, v176, s71, v102
	v_lshl_add_u64 v[98:99], v[98:99], 0, s[100:101]
	v_cvt_pk_bf16_f32 v100, v177, v176
	global_store_dword v[98:99], v100, off
	v_lshlrev_b32_e32 v101, 16, v8
	v_and_b32_e32 v102, 0xffff0000, v8
	v_readlane_b32 s71, v241, 7
	v_fma_f32 v177, v177, s70, v101
	v_fma_f32 v176, v176, s70, v102
	v_lshl_add_u64 v[98:99], v[98:99], 0, s[100:101]
	v_cvt_pk_bf16_f32 v100, v177, v176
	global_store_dword v[98:99], v100, off
	v_lshlrev_b32_e32 v101, 16, v9
	v_and_b32_e32 v102, 0xffff0000, v9
	v_readlane_b32 s70, v241, 8
	v_fma_f32 v177, v177, s71, v101
	v_fma_f32 v176, v176, s71, v102
	v_lshl_add_u64 v[98:99], v[98:99], 0, s[100:101]
	v_cvt_pk_bf16_f32 v100, v177, v176
	global_store_dword v[98:99], v100, off
	v_lshlrev_b32_e32 v101, 16, v10
	v_and_b32_e32 v102, 0xffff0000, v10
	v_readlane_b32 s71, v241, 9
	v_fma_f32 v177, v177, s70, v101
	v_fma_f32 v176, v176, s70, v102
	v_lshl_add_u64 v[98:99], v[98:99], 0, s[100:101]
	v_cvt_pk_bf16_f32 v100, v177, v176
	global_store_dword v[98:99], v100, off
	v_lshlrev_b32_e32 v101, 16, v11
	v_and_b32_e32 v102, 0xffff0000, v11
	v_readlane_b32 s70, v241, 10
	v_fma_f32 v177, v177, s71, v101
	v_fma_f32 v176, v176, s71, v102
	v_lshl_add_u64 v[98:99], v[98:99], 0, s[100:101]
	v_cvt_pk_bf16_f32 v100, v177, v176
	global_store_dword v[98:99], v100, off
	v_lshlrev_b32_e32 v101, 16, v12
	v_and_b32_e32 v102, 0xffff0000, v12
	v_readlane_b32 s71, v241, 11
	v_fma_f32 v177, v177, s70, v101
	v_fma_f32 v176, v176, s70, v102
	v_lshl_add_u64 v[98:99], v[98:99], 0, s[100:101]
	v_cvt_pk_bf16_f32 v100, v177, v176
	global_store_dword v[98:99], v100, off
	v_lshlrev_b32_e32 v101, 16, v13
	v_and_b32_e32 v102, 0xffff0000, v13
	v_readlane_b32 s70, v241, 12
	v_fma_f32 v177, v177, s71, v101
	v_fma_f32 v176, v176, s71, v102
	v_lshl_add_u64 v[98:99], v[98:99], 0, s[100:101]
	v_cvt_pk_bf16_f32 v100, v177, v176
	global_store_dword v[98:99], v100, off
	v_lshlrev_b32_e32 v101, 16, v14
	v_and_b32_e32 v102, 0xffff0000, v14
	v_readlane_b32 s71, v241, 13
	v_fma_f32 v177, v177, s70, v101
	v_fma_f32 v176, v176, s70, v102
	v_lshl_add_u64 v[98:99], v[98:99], 0, s[100:101]
	v_cvt_pk_bf16_f32 v100, v177, v176
	global_store_dword v[98:99], v100, off
	v_lshlrev_b32_e32 v101, 16, v15
	v_and_b32_e32 v102, 0xffff0000, v15
	v_readlane_b32 s70, v241, 14
	v_fma_f32 v177, v177, s71, v101
	v_fma_f32 v176, v176, s71, v102
	v_lshl_add_u64 v[98:99], v[98:99], 0, s[100:101]
	v_cvt_pk_bf16_f32 v100, v177, v176
	global_store_dword v[98:99], v100, off
	v_lshlrev_b32_e32 v101, 16, v16
	v_and_b32_e32 v102, 0xffff0000, v16
	v_readlane_b32 s71, v241, 15
	v_fma_f32 v177, v177, s70, v101
	v_fma_f32 v176, v176, s70, v102
	v_lshl_add_u64 v[98:99], v[98:99], 0, s[100:101]
	v_cvt_pk_bf16_f32 v100, v177, v176
	global_store_dword v[98:99], v100, off
	v_lshlrev_b32_e32 v101, 16, v17
	v_and_b32_e32 v102, 0xffff0000, v17
	v_fma_f32 v177, v177, s71, v101
	v_fma_f32 v176, v176, s71, v102

.LBB0_342:
	v_mov_b32_e32 v24, v164
	s_and_b32 s17, s36, 0x7f
	v_readfirstlane_b32 s16, v24
	s_ashr_i32 s28, s16, 6
	s_lshl_b32 s67, s36, 6
	s_mov_b64 s[24:25], s[52:53]
	s_add_u32 s30, s24, s60
	s_addc_u32 s31, s25, s61
	s_mov_b64 s[24:25], s[54:55]
	v_and_b32_e32 v25, 63, v24
	s_add_u32 s24, s24, s62
	v_or_b32_e32 v0, s67, v25
	s_addc_u32 s25, s25, s63
	s_add_i32 s26, s28, s15
	v_ashrrev_i32_e32 v1, 31, v0
	s_ashr_i32 s27, s26, 31
	v_lshlrev_b64 v[0:1], 5, v[0:1]
	s_ashr_i32 s29, s28, 31
	s_lshl_b64 s[26:27], s[26:27], 2
	v_lshl_add_u64 v[0:1], s[22:23], 0, v[0:1]
	s_add_u32 s34, s56, s26
	v_lshl_add_u64 v[0:1], s[28:29], 2, v[0:1]
	s_addc_u32 s35, s57, s27
	global_load_dword v0, v[0:1], off
	s_nop 0
	global_load_dword v1, v163, s[34:35]
	s_add_u32 s34, s58, s26
	s_addc_u32 s35, s59, s27
	global_load_dword v2, v163, s[34:35]
	s_mov_b32 s0, 0xb2a5705f
	v_lshlrev_b32_e32 v128, 2, v25
	v_cmp_gt_u32_e64 s[40:41], 16, v25
	v_xor_b32_e32 v119, 0x80, v128
	s_cmp_eq_u32 s17, 0
	s_waitcnt vmcnt(0)
	v_add_f32_e32 v0, v0, v1
	v_mul_f32_e64 v1, |v0|, s48
	v_fma_f32 v4, |v0|, s48, -v1
	v_rndne_f32_e32 v5, v1
	v_fma_f32 v4, |v0|, s0, v4
	v_sub_f32_e32 v1, v1, v5
	s_waitcnt vmcnt(0)
	v_mov_b32_e32 v206, s36
	v_lshl_add_u32 v206, v206, 3, s28
	v_lshlrev_b32_e32 v206, 14, v206
	v_and_b32_e32 v207, 48, v25
	v_add_u32_e32 v206, v206, v207
	v_and_b32_e32 v207, 15, v24
	v_lshl_add_u32 v206, v207, 8, v206
	v_mov_b32_e32 v207, 0
	s_mov_b32 s100, s37
	s_mov_b32 s101, s38
	v_lshl_add_u64 v[206:207], s[100:101], 0, v[206:207]
	s_mov_b32 s100, 0x1000
	s_mov_b32 s101, 0
	global_load_dwordx4 v[166:169], v[206:207], off sc1
	global_load_dwordx4 v[182:185], v[206:207], off offset:64 sc1
	global_load_dwordx4 v[198:201], v[206:207], off offset:128 sc1
	global_load_dwordx4 v[238:241], v[206:207], off offset:192 sc1
	v_lshl_add_u64 v[206:207], v[206:207], 0, s[100:101]
	global_load_dwordx4 v[170:173], v[206:207], off sc1
	global_load_dwordx4 v[186:189], v[206:207], off offset:64 sc1
	global_load_dwordx4 v[202:205], v[206:207], off offset:128 sc1
	global_load_dwordx4 v[242:245], v[206:207], off offset:192 sc1
	v_lshl_add_u64 v[206:207], v[206:207], 0, s[100:101]
	global_load_dwordx4 v[174:177], v[206:207], off sc1
	global_load_dwordx4 v[190:193], v[206:207], off offset:64 sc1
	global_load_dwordx4 v[230:233], v[206:207], off offset:128 sc1
	global_load_dwordx4 v[246:249], v[206:207], off offset:192 sc1
	v_lshl_add_u64 v[206:207], v[206:207], 0, s[100:101]
	global_load_dwordx4 v[178:181], v[206:207], off sc1
	global_load_dwordx4 v[194:197], v[206:207], off offset:64 sc1
	global_load_dwordx4 v[234:237], v[206:207], off offset:128 sc1
	global_load_dwordx4 v[250:253], v[206:207], off offset:192 sc1
	v_mul_f32_e32 v6, 0x3fb8aa3b, v2
	v_add_f32_e32 v1, v1, v4
	v_cvt_i32_f32_e32 v5, v5
	v_fma_f32 v7, v2, s4, -v6
	v_rndne_f32_e32 v8, v6
	v_exp_f32_e32 v1, v1
	v_fmac_f32_e32 v7, 0x32a5705f, v2
	v_sub_f32_e32 v4, v6, v8
	v_add_f32_e32 v4, v4, v7
	v_cvt_i32_f32_e32 v6, v8
	v_exp_f32_e32 v4, v4
	s_mov_b32 s0, 0x42ce8ed0
	v_ldexp_f32 v1, v1, v5
	v_cmp_ngt_f32_e64 vcc, |v0|, s0
	s_mov_b32 s0, 0xc2b17218
	v_ldexp_f32 v4, v4, v6
	v_cndmask_b32_e32 v1, 0, v1, vcc
	v_cmp_nlt_f32_e64 vcc, |v0|, s0
	v_max_f32_e32 v3, 0, v0
	s_mov_b32 s0, 0x3f2aaaab
	v_cndmask_b32_e32 v5, v220, v1, vcc
	v_add_f32_e32 v6, 1.0, v5
	v_cmp_ngt_f32_e32 vcc, s82, v2
	v_add_f32_e32 v7, -1.0, v6
	v_frexp_mant_f32_e32 v8, v6
	v_cvt_f64_f32_e32 v[0:1], v6
	v_cndmask_b32_e32 v4, 0, v4, vcc
	v_sub_f32_e32 v9, v7, v6
	v_frexp_exp_i32_f64_e32 v0, v[0:1]
	v_cmp_gt_f32_e32 vcc, s0, v8
	v_sub_f32_e32 v7, v5, v7
	v_add_f32_e32 v1, 1.0, v9
	v_subbrev_co_u32_e32 v0, vcc, 0, v0, vcc
	v_add_f32_e32 v1, v7, v1
	v_sub_u32_e32 v7, 0, v0
	v_cvt_f32_i32_e32 v0, v0
	v_ldexp_f32 v6, v6, v7
	v_ldexp_f32 v1, v1, v7
	v_add_f32_e32 v7, -1.0, v6
	v_add_f32_e32 v8, 1.0, v6
	v_add_f32_e32 v9, 1.0, v7
	v_add_f32_e32 v10, -1.0, v8
	v_sub_f32_e32 v9, v6, v9
	v_sub_f32_e32 v6, v6, v10
	v_mul_f32_e32 v10, 0x3f317218, v0
	v_add_f32_e32 v9, v1, v9
	v_add_f32_e32 v1, v1, v6
	s_mov_b32 s0, 0x3f317218
	v_fma_f32 v6, v0, s0, -v10
	v_add_f32_e32 v11, v7, v9
	v_add_f32_e32 v12, v8, v1
	v_fmac_f32_e32 v6, 0xb102e308, v0
	v_sub_f32_e32 v0, v7, v11
	v_sub_f32_e32 v7, v8, v12
	v_rcp_f32_e32 v8, v12
	v_add_f32_e32 v13, v10, v6
	v_add_f32_e32 v1, v1, v7
	v_sub_f32_e32 v7, v13, v10
	v_sub_f32_e32 v6, v6, v7
	v_mul_f32_e32 v7, v11, v8
	v_add_f32_e32 v0, v9, v0
	v_mul_f32_e32 v9, v12, v7
	v_fma_f32 v10, v7, v12, -v9
	v_fmac_f32_e32 v10, v7, v1
	v_add_f32_e32 v14, v9, v10
	v_sub_f32_e32 v15, v11, v14
	v_sub_f32_e32 v9, v14, v9
	v_sub_f32_e32 v11, v11, v15
	v_sub_f32_e32 v9, v9, v10
	v_sub_f32_e32 v10, v11, v14
	v_add_f32_e32 v0, v0, v10
	v_add_f32_e32 v0, v9, v0
	v_add_f32_e32 v9, v15, v0
	v_mul_f32_e32 v10, v8, v9
	v_sub_f32_e32 v11, v15, v9
	v_mul_f32_e32 v14, v12, v10
	v_add_f32_e32 v0, v0, v11
	v_add_f32_e32 v11, v7, v10
	v_fma_f32 v12, v10, v12, -v14
	v_sub_f32_e32 v7, v11, v7
	v_fmac_f32_e32 v12, v10, v1
	v_sub_f32_e32 v1, v10, v7
	v_add_f32_e32 v7, v14, v12
	v_sub_f32_e32 v10, v7, v14
	v_sub_f32_e32 v14, v9, v7
	v_sub_f32_e32 v9, v9, v14
	v_sub_f32_e32 v7, v9, v7
	v_sub_f32_e32 v10, v10, v12
	v_add_f32_e32 v0, v0, v7
	v_add_f32_e32 v0, v10, v0
	v_add_f32_e32 v0, v14, v0
	v_mul_f32_e32 v0, v8, v0
	v_add_f32_e32 v0, v1, v0
	v_add_f32_e32 v1, v11, v0
	v_mul_f32_e32 v7, v1, v1
	v_fmamk_f32 v10, v7, 0x3e9b6dac, v208
	v_sub_f32_e32 v8, v1, v11
	v_ldexp_f32 v9, v1, 1
	v_mul_f32_e32 v1, v1, v7
	v_fmaak_f32 v7, v7, v10, 0x3f2aaada
	v_mul_f32_e32 v1, v1, v7
	v_add_f32_e32 v7, v9, v1
	v_sub_f32_e32 v0, v0, v8
	v_sub_f32_e32 v8, v7, v9
	v_ldexp_f32 v0, v0, 1
	v_sub_f32_e32 v1, v1, v8
	v_add_f32_e32 v0, v0, v1
	v_add_f32_e32 v1, v7, v0
	v_sub_f32_e32 v7, v1, v7
	v_add_f32_e32 v8, v13, v1
	v_sub_f32_e32 v0, v0, v7
	v_sub_f32_e32 v7, v8, v13
	v_sub_f32_e32 v9, v8, v7
	v_sub_f32_e32 v1, v1, v7
	v_add_f32_e32 v7, v6, v0
	v_sub_f32_e32 v9, v13, v9
	v_sub_f32_e32 v10, v7, v6
	v_add_f32_e32 v1, v1, v9
	v_sub_f32_e32 v9, v7, v10
	v_sub_f32_e32 v0, v0, v10
	v_sub_f32_e32 v6, v6, v9
	v_add_f32_e32 v1, v7, v1
	v_add_f32_e32 v0, v0, v6
	v_add_f32_e32 v6, v8, v1
	v_sub_f32_e32 v7, v6, v8
	v_sub_f32_e32 v1, v1, v7
	v_add_f32_e32 v0, v0, v1
	s_mov_b32 s0, 0x7f800000
	v_add_f32_e32 v0, v6, v0
	v_cmp_neq_f32_e32 vcc, s0, v5
	s_mov_b32 s0, 0x33800000
	v_lshlrev_b32_e32 v10, 1, v24
	v_cndmask_b32_e32 v0, v220, v0, vcc
	v_cmp_lt_f32_e64 vcc, |v5|, s0
	s_movk_i32 s0, 0xffc0
	v_ashrrev_i32_e32 v11, 31, v10
	v_cndmask_b32_e32 v0, v0, v5, vcc
	v_cmp_nlt_f32_e32 vcc, s49, v2
	v_add_f32_e32 v0, v3, v0
	v_add_u32_e32 v3, 0xfc, v128
	v_cndmask_b32_e32 v1, v220, v4, vcc
	v_mul_f32_e64 v2, v0, -v1
	v_and_b32_e32 v3, 0xfc, v3
	ds_bpermute_b32 v3, v3, v2
	v_cmp_eq_u32_e32 vcc, 0, v25
	v_lshlrev_b64 v[8:9], 2, v[10:11]
	s_waitcnt lgkmcnt(0)
	v_fma_f32 v1, v0, -v1, v3
	v_cndmask_b32_e32 v1, v1, v2, vcc
	v_add_u32_e32 v2, 0xf8, v128
	v_and_b32_e32 v2, 0xfc, v2
	ds_bpermute_b32 v2, v2, v1
	v_cmp_gt_u32_e32 vcc, 2, v25
	v_add_u32_e32 v3, 0xc0, v128
	s_waitcnt lgkmcnt(0)
	v_add_f32_e32 v2, v1, v2
	v_cndmask_b32_e32 v1, v2, v1, vcc
	v_add_u32_e32 v2, 0xf0, v128
	v_and_b32_e32 v2, 0xfc, v2
	ds_bpermute_b32 v2, v2, v1
	v_cmp_gt_u32_e32 vcc, 4, v25
	s_waitcnt lgkmcnt(0)
	v_add_f32_e32 v2, v1, v2
	v_cndmask_b32_e32 v1, v2, v1, vcc
	v_add_u32_e32 v2, 0xe0, v128
	v_and_b32_e32 v2, 0xfc, v2
	ds_bpermute_b32 v2, v2, v1
	v_cmp_gt_u32_e32 vcc, 8, v25
	s_waitcnt lgkmcnt(0)
	v_add_f32_e32 v2, v1, v2
	v_cndmask_b32_e32 v1, v2, v1, vcc
	v_and_b32_e32 v2, 0xfc, v3
	ds_bpermute_b32 v2, v2, v1
	v_mov_b32_e32 v3, s16
	v_bfi_b32 v3, s0, v3, v24
	v_cmp_gt_u32_e32 vcc, 32, v25
	v_lshl_add_u32 v3, v3, 2, 0
	s_waitcnt lgkmcnt(0)
	v_add_f32_e32 v2, v1, v2
	v_cndmask_b32_e64 v1, v2, v1, s[40:41]
	ds_bpermute_b32 v2, v119, v1
	s_waitcnt lgkmcnt(0)
	v_add_f32_e32 v2, v1, v2
	v_cndmask_b32_e32 v1, v2, v1, vcc
	ds_write2st64_b32 v3, v0, v1 offset1:8
	v_lshl_add_u64 v[0:1], s[30:31], 0, v[8:9]
	v_add_co_u32_e32 v2, vcc, 0x1000, v0
	v_lshl_add_u64 v[8:9], s[24:25], 0, v[8:9]
	s_nop 0
	v_addc_co_u32_e32 v3, vcc, 0, v1, vcc
	v_add_co_u32_e32 v4, vcc, 0x2000, v0
	s_nop 1
	v_addc_co_u32_e32 v5, vcc, 0, v1, vcc
	v_add_co_u32_e32 v6, vcc, 0x3000, v0
	s_nop 1
	v_addc_co_u32_e32 v7, vcc, 0, v1, vcc
	flat_load_dwordx2 v[0:1], v[0:1]
	s_nop 0
	flat_load_dwordx2 v[2:3], v[2:3]
	s_nop 0
	flat_load_dwordx2 v[4:5], v[4:5]
	s_nop 0
	flat_load_dwordx2 v[6:7], v[6:7]
	s_nop 0
	flat_load_dwordx2 v[8:9], v[8:9]
	s_cbranch_scc1 .LBB0_344
	s_mul_i32 s24, s67, 0x1600
	s_mul_hi_i32 s17, s67, 0x1600
	s_add_u32 s24, s20, s24
	s_addc_u32 s25, s21, s17
	v_lshl_add_u64 v[12:13], v[10:11], 1, s[24:25]
	v_add_co_u32_e32 v14, vcc, 0xffffd000, v12
	s_nop 1
	v_addc_co_u32_e32 v15, vcc, -1, v13, vcc
	global_load_dword v16, v[14:15], off offset:-2048
	v_add_co_u32_e32 v14, vcc, 0xffffe000, v12
	s_nop 1
	v_addc_co_u32_e32 v15, vcc, -1, v13, vcc
	global_load_dword v14, v[14:15], off offset:-512
	s_nop 0
	global_load_dword v15, v[12:13], off offset:-3072
	s_waitcnt vmcnt(0)
	v_lshlrev_b32_e32 v12, 16, v16
	v_and_b32_e32 v13, 0xffff0000, v16
	v_lshlrev_b32_e32 v16, 16, v14
	v_and_b32_e32 v17, 0xffff0000, v14
	v_lshlrev_b32_e32 v14, 16, v15
	v_and_b32_e32 v15, 0xffff0000, v15
	s_branch .LBB0_345

.Lmy_xb_poll:
	s_mov_b64 exec, s[14:15]
	s_mov_b32 s3, 0
	s_sub_i32 s18, s68, 1
	s_lshl_b32 s18, 1, s18
	s_and_b32 s18, s18, 0x60c
	s_cmp_lg_u32 s18, 0
	s_cbranch_scc1 .Lmy_xb_noinv2
	buffer_inv sc1
.Lmy_xb_noinv2:
.Lmy_xb_spin:
	global_load_dword v5, v163, s[16:17] sc1
	s_waitcnt vmcnt(0)
	v_cmp_ge_u32_e32 vcc, v5, v4
	s_cbranch_vccnz .Lmy_xb_done
	s_sleep 1
	s_add_i32 s3, s3, 1
	s_cmp_lt_u32 s3, 0x20000
	s_cbranch_scc1 .Lmy_xb_spin
